# wkv first-item row loads batched (10 in flight); attention xor-32 exchanges via v_permlane32_swap instead of ds_bpermute
# speedup vs baseline: 1.0832x; 1.0078x over previous
.LBB0_757:
	s_cmpk_lt_i32 s90, 0x1000
	v_mov_b32_e32 v120, v174
	s_cselect_b64 s[0:1], -1, 0
	s_cmpk_gt_i32 s90, 0xfff
	s_cbranch_scc1 .LBB0_769
	v_mov_b32_e32 v0, v174
	s_lshl_b32 s2, s90, 6
	v_ashrrev_i32_e32 v4, 3, v0
	v_lshlrev_b32_e32 v0, 3, v0
	v_and_b32_e32 v28, 56, v0
	s_and_b32 s2, s2, 0x1c0
	v_readlane_b32 s4, v241, 16
	v_readlane_b32 s36, v240, 1
	v_or_b32_e32 v2, s2, v28
	s_and_b32 s2, s4, 0xffffffc0
	v_readlane_b32 s40, v240, 5
	v_readlane_b32 s41, v240, 6
	v_add_u32_e32 v3, s2, v4
	s_movk_i32 s2, 0x1040
	v_mov_b64_e32 v[0:1], s[40:41]
	v_mad_i64_i32 v[24:25], s[2:3], v3, s2, v[0:1]
	v_lshlrev_b32_e32 v0, 1, v2
	v_mov_b32_e32 v1, 0
	v_lshl_add_u64 v[26:27], v[24:25], 0, v[0:1]
	global_load_dwordx4 v[0:3], v[26:27], off offset:832
	s_and_b32 s2, s4, 0xfc0
	v_add_u32_e32 v4, s2, v4
	v_cmp_lt_i32_e32 vcc, 0, v4
	v_readlane_b32 s37, v240, 2
	v_readlane_b32 s38, v240, 3
	v_readlane_b32 s39, v240, 4
	v_readlane_b32 s42, v240, 7
	v_readlane_b32 s43, v240, 8
	v_readlane_b32 s44, v240, 9
	v_readlane_b32 s45, v240, 10
	v_readlane_b32 s46, v240, 11
	v_readlane_b32 s47, v240, 12
	v_readlane_b32 s48, v240, 13
	v_readlane_b32 s49, v240, 14
	v_readlane_b32 s50, v240, 15
	v_readlane_b32 s51, v240, 16
	global_load_dwordx4 v[8:11], v[26:27], off offset:1856
	global_load_dwordx4 v[16:19], v[26:27], off offset:2880
	s_and_saveexec_b64 s[4:5], vcc
	global_load_dwordx4 v[4:7], v[26:27], off offset:-3328
	global_load_dwordx4 v[12:15], v[26:27], off offset:-2304
	global_load_dwordx4 v[20:23], v[26:27], off offset:-1280
	s_or_b64 exec, exec, s[4:5]
	v_lshlrev_b32_e32 v26, 1, v28
	v_mov_b32_e32 v27, 0
	v_lshl_add_u64 v[40:41], v[24:25], 0, v[26:27]
	s_and_saveexec_b64 s[4:5], vcc
	global_load_dwordx4 v[28:31], v[40:41], off offset:-256
	global_load_dwordx4 v[36:39], v[40:41], off offset:-128
	s_or_b64 exec, exec, s[4:5]
	global_load_dwordx4 v[24:27], v[40:41], off offset:3904
	global_load_dwordx4 v[32:35], v[40:41], off offset:4032
	s_branch .LBB0_770

.LBB0_1046:
	s_or_b64 exec, exec, s[22:23]
	global_load_dwordx4 v[152:155], v[168:169], off
	s_and_b32 s25, s4, 1
	v_cmp_le_i32_e32 vcc, s4, v185
	s_and_saveexec_b64 s[22:23], vcc
	s_cbranch_execz .LBB0_1052
	s_mul_i32 s26, s25, 0x5600
	s_add_i32 s26, s26, 0
	v_add3_u32 v187, s26, v184, v166
	ds_read_b128 v[64:67], v187
	ds_read_b128 v[188:191], v187 offset:32
	v_and_b32_e32 v200, 64, v175
	v_add_u32_e32 v200, 64, v200
	s_waitcnt lgkmcnt(1)
	v_mfma_f32_32x32x16_bf16 v[80:95], v[64:67], v[132:135], 0
	v_mfma_f32_32x32x16_bf16 v[64:79], v[64:67], v[140:143], 0
	s_waitcnt lgkmcnt(0)
	v_mfma_f32_32x32x16_bf16 v[80:95], v[188:191], v[124:127], v[80:95]
	v_mfma_f32_32x32x16_bf16 v[64:79], v[188:191], v[136:139], v[64:79]
	ds_read_b128 v[188:191], v187 offset:64
	ds_read_b128 v[192:195], v187 offset:96
	s_waitcnt lgkmcnt(1)
	v_mfma_f32_32x32x16_bf16 v[80:95], v[188:191], v[120:123], v[80:95]
	s_waitcnt lgkmcnt(0)
	v_mfma_f32_32x32x16_bf16 v[80:95], v[192:195], v[116:119], v[80:95]
	v_mfma_f32_32x32x16_bf16 v[64:79], v[188:191], v[128:131], v[64:79]
	ds_read_b128 v[188:191], v187 offset:128
	ds_read_b128 v[196:199], v187 offset:160
	v_xor_b32_e32 v187, 32, v175
	v_cmp_lt_i32_e32 vcc, v187, v200
	s_nop 1
	v_cndmask_b32_e32 v187, v175, v187, vcc
	v_lshlrev_b32_e32 v187, 2, v187
	s_waitcnt lgkmcnt(1)
	v_mfma_f32_32x32x16_bf16 v[80:95], v[188:191], v[112:115], v[80:95]
	s_waitcnt lgkmcnt(0)
	v_mfma_f32_32x32x16_bf16 v[80:95], v[196:199], v[108:111], v[80:95]
	v_mfma_f32_32x32x16_bf16 v[64:79], v[192:195], v[104:107], v[64:79]
	s_nop 10
	v_max_f32_e32 v200, v81, v81
	v_max_f32_e32 v192, v80, v80
	v_max_f32_e32 v192, v192, v200
	v_max3_f32 v192, v192, v82, v83
	v_max3_f32 v192, v192, v84, v85
	v_max3_f32 v192, v192, v86, v87
	v_max3_f32 v192, v192, v88, v89
	v_mfma_f32_32x32x16_bf16 v[64:79], v[188:191], v[100:103], v[64:79]
	v_max3_f32 v192, v192, v90, v91
	v_max3_f32 v188, v192, v92, v93
	v_max3_f32 v188, v188, v94, v95
	v_mov_b32_e32 v189, v188
	s_nop 1
	v_permlane32_swap_b32_e32 v189, v188
	s_waitcnt lgkmcnt(0)
	v_max_f32_e32 v189, v189, v189
	v_mfma_f32_32x32x16_bf16 v[64:79], v[196:199], v[96:99], v[64:79]
	v_max_f32_e32 v188, v188, v189
	v_add_f32_e32 v189, 0x41000000, v161
	v_cmp_gt_f32_e32 vcc, v188, v189
	s_cbranch_vccz .LBB0_1049
	v_max_f32_e32 v188, v188, v188
	v_max_f32_e32 v189, v161, v161
	v_max_f32_e32 v189, v189, v188
	v_sub_f32_e32 v161, v161, v189
	v_exp_f32_e32 v188, v161
	v_mov_b32_e32 v161, v189
	v_mul_f32_e32 v162, v162, v188
	v_pk_mul_f32 v[62:63], v[62:63], v[188:189] op_sel_hi:[1,0]
	v_pk_mul_f32 v[60:61], v[60:61], v[188:189] op_sel_hi:[1,0]
	v_pk_mul_f32 v[58:59], v[58:59], v[188:189] op_sel_hi:[1,0]
	v_pk_mul_f32 v[56:57], v[56:57], v[188:189] op_sel_hi:[1,0]
	v_pk_mul_f32 v[54:55], v[54:55], v[188:189] op_sel_hi:[1,0]
	v_pk_mul_f32 v[52:53], v[52:53], v[188:189] op_sel_hi:[1,0]
	v_pk_mul_f32 v[50:51], v[50:51], v[188:189] op_sel_hi:[1,0]
	v_pk_mul_f32 v[48:49], v[48:49], v[188:189] op_sel_hi:[1,0]
	v_pk_mul_f32 v[46:47], v[46:47], v[188:189] op_sel_hi:[1,0]
	v_pk_mul_f32 v[44:45], v[44:45], v[188:189] op_sel_hi:[1,0]
	v_pk_mul_f32 v[42:43], v[42:43], v[188:189] op_sel_hi:[1,0]
	v_pk_mul_f32 v[40:41], v[40:41], v[188:189] op_sel_hi:[1,0]
	v_pk_mul_f32 v[38:39], v[38:39], v[188:189] op_sel_hi:[1,0]
	v_pk_mul_f32 v[36:37], v[36:37], v[188:189] op_sel_hi:[1,0]
	v_pk_mul_f32 v[34:35], v[34:35], v[188:189] op_sel_hi:[1,0]
	v_pk_mul_f32 v[32:33], v[32:33], v[188:189] op_sel_hi:[1,0]
.LBB0_1049:
	v_sub_f32_e32 v188, v95, v161
	v_sub_f32_e32 v189, v94, v161
	v_sub_f32_e32 v192, v91, v161
	v_sub_f32_e32 v193, v90, v161
	v_sub_f32_e32 v87, v87, v161
	v_sub_f32_e32 v86, v86, v161
	v_sub_f32_e32 v83, v83, v161
	v_sub_f32_e32 v82, v82, v161
	v_exp_f32_e32 v90, v82
	v_exp_f32_e32 v91, v83
	v_exp_f32_e32 v94, v86
	v_exp_f32_e32 v95, v87
	v_exp_f32_e32 v82, v193
	v_exp_f32_e32 v86, v189
	v_exp_f32_e32 v87, v188
	v_exp_f32_e32 v83, v192
	v_sub_f32_e32 v194, v89, v161
	v_sub_f32_e32 v195, v88, v161
	v_sub_f32_e32 v81, v81, v161
	v_sub_f32_e32 v80, v80, v161
	v_exp_f32_e32 v88, v80
	v_exp_f32_e32 v89, v81
	v_exp_f32_e32 v80, v195
	v_exp_f32_e32 v81, v194
	v_pk_add_f32 v[192:193], v[94:95], v[86:87]
	v_pk_add_f32 v[194:195], v[90:91], v[82:83]
	v_sub_f32_e32 v190, v93, v161
	v_pk_add_f32 v[192:193], v[194:195], v[192:193]
	v_max_f32_e32 v194, v65, v65
	v_max_f32_e32 v195, v64, v64
	v_max_f32_e32 v194, v195, v194
	v_max3_f32 v194, v194, v66, v67
	v_sub_f32_e32 v191, v92, v161
	v_sub_f32_e32 v85, v85, v161
	v_sub_f32_e32 v84, v84, v161
	v_max3_f32 v194, v194, v68, v69
	v_exp_f32_e32 v92, v84
	v_exp_f32_e32 v93, v85
	v_exp_f32_e32 v84, v191
	v_exp_f32_e32 v85, v190
	v_max3_f32 v194, v194, v70, v71
	v_max3_f32 v194, v194, v72, v73
	v_max3_f32 v194, v194, v74, v75
	v_max3_f32 v194, v194, v76, v77
	v_pk_add_f32 v[188:189], v[92:93], v[84:85]
	v_pk_add_f32 v[190:191], v[88:89], v[80:81]
	v_max3_f32 v194, v194, v78, v79
	v_mov_b32_e32 v195, v194
	s_nop 1
	v_permlane32_swap_b32_e32 v195, v194
	v_pk_add_f32 v[188:189], v[190:191], v[188:189]
	v_add_f32_e32 v191, 0x41000000, v167
	v_pk_add_f32 v[188:189], v[188:189], v[192:193]
	s_waitcnt lgkmcnt(0)
	v_max_f32_e32 v190, v195, v195
	v_add_f32_e32 v188, v188, v189
	v_mov_b32_e32 v189, v188
	s_nop 1
	v_permlane32_swap_b32_e32 v189, v188
	v_max_f32_e32 v190, v194, v190
	v_cmp_gt_f32_e32 vcc, v190, v191
	s_cbranch_vccz .LBB0_1051
	v_max_f32_e32 v190, v190, v190
	v_max_f32_e32 v191, v167, v167
	v_max_f32_e32 v191, v191, v190
	v_sub_f32_e32 v167, v167, v191
	v_exp_f32_e32 v190, v167
	v_mov_b32_e32 v167, v191
	v_mul_f32_e32 v160, v160, v190
	v_pk_mul_f32 v[30:31], v[30:31], v[190:191] op_sel_hi:[1,0]
	v_pk_mul_f32 v[28:29], v[28:29], v[190:191] op_sel_hi:[1,0]
	v_pk_mul_f32 v[26:27], v[26:27], v[190:191] op_sel_hi:[1,0]
	v_pk_mul_f32 v[24:25], v[24:25], v[190:191] op_sel_hi:[1,0]
	v_pk_mul_f32 v[22:23], v[22:23], v[190:191] op_sel_hi:[1,0]
	v_pk_mul_f32 v[20:21], v[20:21], v[190:191] op_sel_hi:[1,0]
	v_pk_mul_f32 v[18:19], v[18:19], v[190:191] op_sel_hi:[1,0]
	v_pk_mul_f32 v[16:17], v[16:17], v[190:191] op_sel_hi:[1,0]
	v_pk_mul_f32 v[14:15], v[14:15], v[190:191] op_sel_hi:[1,0]
	v_pk_mul_f32 v[12:13], v[12:13], v[190:191] op_sel_hi:[1,0]
	v_pk_mul_f32 v[10:11], v[10:11], v[190:191] op_sel_hi:[1,0]
	v_pk_mul_f32 v[8:9], v[8:9], v[190:191] op_sel_hi:[1,0]
	v_pk_mul_f32 v[6:7], v[6:7], v[190:191] op_sel_hi:[1,0]
	v_pk_mul_f32 v[4:5], v[4:5], v[190:191] op_sel_hi:[1,0]
	v_pk_mul_f32 v[2:3], v[2:3], v[190:191] op_sel_hi:[1,0]
	v_pk_mul_f32 v[0:1], v[0:1], v[190:191] op_sel_hi:[1,0]
.LBB0_1051:
	v_lshl_add_u32 v191, v179, 1, s26
	v_add3_u32 v198, v191, v158, v178
	v_sub_f32_e32 v64, v64, v167
	v_add_u32_e32 v199, 0x3000, v198
	v_sub_f32_e32 v196, v71, v167
	v_sub_f32_e32 v197, v70, v167
	v_sub_f32_e32 v195, v69, v167
	v_sub_f32_e32 v69, v67, v167
	v_sub_f32_e32 v70, v66, v167
	v_sub_f32_e32 v71, v65, v167
	v_exp_f32_e32 v190, v64
	ds_read2_b64 v[64:67], v199 offset0:128 offset1:130
	v_sub_f32_e32 v68, v68, v167
	v_exp_f32_e32 v191, v71
	v_exp_f32_e32 v192, v70
	v_exp_f32_e32 v193, v69
	v_exp_f32_e32 v194, v68
	v_cvt_pk_bf16_f32 v70, v92, v93
	v_exp_f32_e32 v195, v195
	v_exp_f32_e32 v92, v197
	v_exp_f32_e32 v93, v196
	v_cvt_pk_bf16_f32 v68, v88, v89
	v_cvt_pk_bf16_f32 v69, v90, v91
	v_cvt_pk_bf16_f32 v71, v94, v95
	v_cvt_pk_bf16_f32 v88, v190, v191
	v_cvt_pk_bf16_f32 v89, v192, v193
	v_cvt_pk_bf16_f32 v90, v194, v195
	v_cvt_pk_bf16_f32 v91, v92, v93
	v_add_u32_e32 v198, 0x4000, v198
	s_waitcnt lgkmcnt(0)
	v_mfma_f32_32x32x16_bf16 v[48:63], v[64:67], v[68:71], v[48:63]
	v_sub_f32_e32 v79, v79, v167
	v_sub_f32_e32 v78, v78, v167
	v_sub_f32_e32 v77, v77, v167
	v_sub_f32_e32 v76, v76, v167
	v_sub_f32_e32 v75, v75, v167
	v_sub_f32_e32 v74, v74, v167
	v_exp_f32_e32 v196, v74
	v_mfma_f32_32x32x16_bf16 v[16:31], v[64:67], v[88:91], v[16:31]
	ds_read2_b64 v[64:67], v198 offset0:160 offset1:162
	v_exp_f32_e32 v197, v75
	v_exp_f32_e32 v74, v76
	v_exp_f32_e32 v75, v77
	s_waitcnt lgkmcnt(0)
	v_mfma_f32_32x32x16_bf16 v[32:47], v[64:67], v[68:71], v[32:47]
	v_sub_f32_e32 v68, v73, v167
	v_sub_f32_e32 v69, v72, v167
	v_exp_f32_e32 v94, v69
	v_exp_f32_e32 v95, v68
	ds_read2_b64 v[68:71], v199 offset0:132 offset1:134
	v_cvt_pk_bf16_f32 v73, v196, v197
	v_cvt_pk_bf16_f32 v72, v94, v95
	v_mfma_f32_32x32x16_bf16 v[0:15], v[64:67], v[88:91], v[0:15]
	v_exp_f32_e32 v88, v78
	v_exp_f32_e32 v89, v79
	ds_read2_b64 v[76:79], v198 offset0:164 offset1:166
	v_cvt_pk_bf16_f32 v64, v80, v81
	v_cvt_pk_bf16_f32 v65, v82, v83
	v_cvt_pk_bf16_f32 v66, v84, v85
	v_cvt_pk_bf16_f32 v67, v86, v87
	v_pk_add_f32 v[80:81], v[194:195], v[74:75]
	v_cvt_pk_bf16_f32 v74, v74, v75
	v_cvt_pk_bf16_f32 v75, v88, v89
	s_waitcnt lgkmcnt(1)
	v_mfma_f32_32x32x16_bf16 v[48:63], v[68:71], v[64:67], v[48:63]
	v_add_f32_e64 v82, v192, v196
	v_add_f32_e64 v83, v193, v197
	v_mfma_f32_32x32x16_bf16 v[16:31], v[68:71], v[72:75], v[16:31]
	v_add_f32_e64 v68, v190, v94
	v_add_f32_e64 v69, v191, v95
	v_add_f32_e64 v70, v92, v88
	v_add_f32_e64 v71, v93, v89
	v_add_f32_e64 v68, v68, v80
	v_add_f32_e64 v69, v69, v81
	v_pk_add_f32 v[70:71], v[82:83], v[70:71]
	s_nop 0
	v_pk_add_f32 v[68:69], v[68:69], v[70:71]
	s_nop 0
	v_add_f32_e32 v68, v68, v69
	s_waitcnt lgkmcnt(0)
	v_mfma_f32_32x32x16_bf16 v[32:47], v[76:79], v[64:67], v[32:47]
	v_mov_b32_e32 v64, v68
	s_nop 1
	v_permlane32_swap_b32_e32 v64, v68
	v_add_f32_e32 v65, v188, v189
	v_add_f32_e32 v162, v162, v65
	s_waitcnt lgkmcnt(0)
	v_add_f32_e32 v64, v68, v64
	v_add_f32_e32 v160, v160, v64
	v_mfma_f32_32x32x16_bf16 v[0:15], v[76:79], v[72:75], v[0:15]

.LBB0_1054:
	v_cmp_lt_i32_e32 vcc, 2, v163
	s_and_saveexec_b64 s[0:1], vcc
	s_cbranch_execz .LBB0_1060
	s_bitcmp1_b32 s24, 0
	s_cselect_b32 s4, 0x5600, 0
	s_add_i32 s4, s4, 0
	v_add3_u32 v148, s4, v184, v166
	ds_read_b128 v[64:67], v148
	ds_read_b128 v[144:147], v148 offset:32
	s_waitcnt lgkmcnt(1)
	v_mfma_f32_32x32x16_bf16 v[80:95], v[64:67], v[132:135], 0
	s_waitcnt lgkmcnt(0)
	v_mfma_f32_32x32x16_bf16 v[80:95], v[144:147], v[124:127], v[80:95]
	ds_read_b128 v[124:127], v148 offset:64
	ds_read_b128 v[132:135], v148 offset:96
	s_waitcnt lgkmcnt(1)
	v_mfma_f32_32x32x16_bf16 v[80:95], v[124:127], v[120:123], v[80:95]
	v_mfma_f32_32x32x16_bf16 v[64:79], v[64:67], v[140:143], 0
	s_waitcnt lgkmcnt(0)
	v_mfma_f32_32x32x16_bf16 v[80:95], v[132:135], v[116:119], v[80:95]
	ds_read_b128 v[116:119], v148 offset:128
	ds_read_b128 v[120:123], v148 offset:160
	v_mfma_f32_32x32x16_bf16 v[64:79], v[144:147], v[136:139], v[64:79]
	s_waitcnt lgkmcnt(1)
	v_mfma_f32_32x32x16_bf16 v[80:95], v[116:119], v[112:115], v[80:95]
	v_mfma_f32_32x32x16_bf16 v[64:79], v[124:127], v[128:131], v[64:79]
	s_waitcnt lgkmcnt(0)
	v_mfma_f32_32x32x16_bf16 v[80:95], v[120:123], v[108:111], v[80:95]
	v_and_b32_e32 v109, 64, v175
	v_xor_b32_e32 v108, 32, v175
	v_add_u32_e32 v109, 64, v109
	v_cmp_lt_i32_e32 vcc, v108, v109
	s_nop 1
	v_cndmask_b32_e32 v108, v175, v108, vcc
	v_mfma_f32_32x32x16_bf16 v[64:79], v[132:135], v[104:107], v[64:79]
	s_nop 3
	v_max_f32_e32 v109, v81, v81
	v_max_f32_e32 v104, v80, v80
	v_max_f32_e32 v104, v104, v109
	v_max3_f32 v104, v104, v82, v83
	v_max3_f32 v104, v104, v84, v85
	v_max3_f32 v104, v104, v86, v87
	v_max3_f32 v104, v104, v88, v89
	v_mfma_f32_32x32x16_bf16 v[64:79], v[116:119], v[100:103], v[64:79]
	v_max3_f32 v104, v104, v90, v91
	v_max3_f32 v100, v104, v92, v93
	v_lshlrev_b32_e32 v108, 2, v108
	v_max3_f32 v100, v100, v94, v95
	v_mov_b32_e32 v101, v100
	s_nop 1
	v_permlane32_swap_b32_e32 v101, v100
	s_waitcnt lgkmcnt(0)
	v_max_f32_e32 v101, v101, v101
	v_mfma_f32_32x32x16_bf16 v[64:79], v[120:123], v[96:99], v[64:79]
	v_max_f32_e32 v100, v100, v101
	v_add_f32_e32 v101, 0x41000000, v161
	v_cmp_gt_f32_e32 vcc, v100, v101
	s_cbranch_vccz .LBB0_1057
	v_max_f32_e32 v96, v100, v100
	v_max_f32_e32 v97, v161, v161
	v_max_f32_e32 v97, v97, v96
	v_sub_f32_e32 v96, v161, v97
	v_exp_f32_e32 v96, v96
	v_mov_b32_e32 v161, v97
	v_mul_f32_e32 v162, v162, v96
	v_pk_mul_f32 v[62:63], v[62:63], v[96:97] op_sel_hi:[1,0]
	v_pk_mul_f32 v[60:61], v[60:61], v[96:97] op_sel_hi:[1,0]
	v_pk_mul_f32 v[58:59], v[58:59], v[96:97] op_sel_hi:[1,0]
	v_pk_mul_f32 v[56:57], v[56:57], v[96:97] op_sel_hi:[1,0]
	v_pk_mul_f32 v[54:55], v[54:55], v[96:97] op_sel_hi:[1,0]
	v_pk_mul_f32 v[52:53], v[52:53], v[96:97] op_sel_hi:[1,0]
	v_pk_mul_f32 v[50:51], v[50:51], v[96:97] op_sel_hi:[1,0]
	v_pk_mul_f32 v[48:49], v[48:49], v[96:97] op_sel_hi:[1,0]
	v_pk_mul_f32 v[46:47], v[46:47], v[96:97] op_sel_hi:[1,0]
	v_pk_mul_f32 v[44:45], v[44:45], v[96:97] op_sel_hi:[1,0]
	v_pk_mul_f32 v[42:43], v[42:43], v[96:97] op_sel_hi:[1,0]
	v_pk_mul_f32 v[40:41], v[40:41], v[96:97] op_sel_hi:[1,0]
	v_pk_mul_f32 v[38:39], v[38:39], v[96:97] op_sel_hi:[1,0]
	v_pk_mul_f32 v[36:37], v[36:37], v[96:97] op_sel_hi:[1,0]
	v_pk_mul_f32 v[34:35], v[34:35], v[96:97] op_sel_hi:[1,0]
	v_pk_mul_f32 v[32:33], v[32:33], v[96:97] op_sel_hi:[1,0]
.LBB0_1057:
	v_sub_f32_e32 v96, v95, v161
	v_sub_f32_e32 v97, v94, v161
	v_sub_f32_e32 v100, v91, v161
	v_sub_f32_e32 v101, v90, v161
	v_sub_f32_e32 v87, v87, v161
	v_sub_f32_e32 v86, v86, v161
	v_sub_f32_e32 v83, v83, v161
	v_sub_f32_e32 v82, v82, v161
	v_exp_f32_e32 v90, v82
	v_exp_f32_e32 v91, v83
	v_exp_f32_e32 v94, v86
	v_exp_f32_e32 v95, v87
	v_exp_f32_e32 v82, v101
	v_exp_f32_e32 v86, v97
	v_exp_f32_e32 v87, v96
	v_exp_f32_e32 v83, v100
	v_sub_f32_e32 v102, v89, v161
	v_sub_f32_e32 v103, v88, v161
	v_sub_f32_e32 v81, v81, v161
	v_sub_f32_e32 v80, v80, v161
	v_exp_f32_e32 v88, v80
	v_exp_f32_e32 v89, v81
	v_exp_f32_e32 v80, v103
	v_exp_f32_e32 v81, v102
	v_pk_add_f32 v[100:101], v[94:95], v[86:87]
	v_pk_add_f32 v[102:103], v[90:91], v[82:83]
	v_sub_f32_e32 v98, v93, v161
	v_pk_add_f32 v[100:101], v[102:103], v[100:101]
	v_max_f32_e32 v102, v65, v65
	v_max_f32_e32 v103, v64, v64
	v_max_f32_e32 v102, v103, v102
	v_max3_f32 v102, v102, v66, v67
	v_sub_f32_e32 v99, v92, v161
	v_sub_f32_e32 v85, v85, v161
	v_sub_f32_e32 v84, v84, v161
	v_max3_f32 v102, v102, v68, v69
	v_exp_f32_e32 v92, v84
	v_exp_f32_e32 v93, v85
	v_exp_f32_e32 v84, v99
	v_exp_f32_e32 v85, v98
	v_max3_f32 v102, v102, v70, v71
	v_max3_f32 v102, v102, v72, v73
	v_max3_f32 v102, v102, v74, v75
	v_max3_f32 v102, v102, v76, v77
	v_pk_add_f32 v[96:97], v[92:93], v[84:85]
	v_pk_add_f32 v[98:99], v[88:89], v[80:81]
	v_max3_f32 v102, v102, v78, v79
	v_mov_b32_e32 v103, v102
	s_nop 1
	v_permlane32_swap_b32_e32 v103, v102
	v_pk_add_f32 v[96:97], v[98:99], v[96:97]
	v_add_f32_e32 v99, 0x41000000, v167
	v_pk_add_f32 v[96:97], v[96:97], v[100:101]
	s_waitcnt lgkmcnt(0)
	v_max_f32_e32 v98, v103, v103
	v_add_f32_e32 v96, v96, v97
	v_mov_b32_e32 v97, v96
	s_nop 1
	v_permlane32_swap_b32_e32 v97, v96
	v_max_f32_e32 v98, v102, v98
	v_cmp_gt_f32_e32 vcc, v98, v99
	s_cbranch_vccz .LBB0_1059
	v_max_f32_e32 v98, v98, v98
	v_max_f32_e32 v99, v167, v167
	v_max_f32_e32 v99, v99, v98
	v_sub_f32_e32 v98, v167, v99
	v_exp_f32_e32 v98, v98
	v_mov_b32_e32 v167, v99
	v_mul_f32_e32 v160, v160, v98
	v_pk_mul_f32 v[30:31], v[30:31], v[98:99] op_sel_hi:[1,0]
	v_pk_mul_f32 v[28:29], v[28:29], v[98:99] op_sel_hi:[1,0]
	v_pk_mul_f32 v[26:27], v[26:27], v[98:99] op_sel_hi:[1,0]
	v_pk_mul_f32 v[24:25], v[24:25], v[98:99] op_sel_hi:[1,0]
	v_pk_mul_f32 v[22:23], v[22:23], v[98:99] op_sel_hi:[1,0]
	v_pk_mul_f32 v[20:21], v[20:21], v[98:99] op_sel_hi:[1,0]
	v_pk_mul_f32 v[18:19], v[18:19], v[98:99] op_sel_hi:[1,0]
	v_pk_mul_f32 v[16:17], v[16:17], v[98:99] op_sel_hi:[1,0]
	v_pk_mul_f32 v[14:15], v[14:15], v[98:99] op_sel_hi:[1,0]
	v_pk_mul_f32 v[12:13], v[12:13], v[98:99] op_sel_hi:[1,0]
	v_pk_mul_f32 v[10:11], v[10:11], v[98:99] op_sel_hi:[1,0]
	v_pk_mul_f32 v[8:9], v[8:9], v[98:99] op_sel_hi:[1,0]
	v_pk_mul_f32 v[6:7], v[6:7], v[98:99] op_sel_hi:[1,0]
	v_pk_mul_f32 v[4:5], v[4:5], v[98:99] op_sel_hi:[1,0]
	v_pk_mul_f32 v[2:3], v[2:3], v[98:99] op_sel_hi:[1,0]
	v_pk_mul_f32 v[0:1], v[0:1], v[98:99] op_sel_hi:[1,0]
.LBB0_1059:
	v_lshl_add_u32 v99, v179, 1, s4
	v_add3_u32 v106, v99, v158, v178
	v_sub_f32_e32 v64, v64, v167
	v_add_u32_e32 v107, 0x3000, v106
	v_sub_f32_e32 v104, v71, v167
	v_sub_f32_e32 v105, v70, v167
	v_sub_f32_e32 v103, v69, v167
	v_sub_f32_e32 v69, v67, v167
	v_sub_f32_e32 v70, v66, v167
	v_sub_f32_e32 v71, v65, v167
	v_exp_f32_e32 v98, v64
	ds_read2_b64 v[64:67], v107 offset0:128 offset1:130
	v_sub_f32_e32 v68, v68, v167
	v_exp_f32_e32 v99, v71
	v_exp_f32_e32 v100, v70
	v_exp_f32_e32 v101, v69
	v_exp_f32_e32 v102, v68
	v_cvt_pk_bf16_f32 v70, v92, v93
	v_exp_f32_e32 v103, v103
	v_exp_f32_e32 v92, v105
	v_exp_f32_e32 v93, v104
	v_cvt_pk_bf16_f32 v68, v88, v89
	v_cvt_pk_bf16_f32 v69, v90, v91
	v_cvt_pk_bf16_f32 v71, v94, v95
	v_cvt_pk_bf16_f32 v88, v98, v99
	v_cvt_pk_bf16_f32 v89, v100, v101
	v_cvt_pk_bf16_f32 v90, v102, v103
	v_cvt_pk_bf16_f32 v91, v92, v93
	v_add_u32_e32 v106, 0x4000, v106
	s_waitcnt lgkmcnt(0)
	v_mfma_f32_32x32x16_bf16 v[48:63], v[64:67], v[68:71], v[48:63]
	v_sub_f32_e32 v79, v79, v167
	v_sub_f32_e32 v78, v78, v167
	v_sub_f32_e32 v77, v77, v167
	v_sub_f32_e32 v76, v76, v167
	v_sub_f32_e32 v75, v75, v167
	v_sub_f32_e32 v74, v74, v167
	v_exp_f32_e32 v104, v74
	v_mfma_f32_32x32x16_bf16 v[16:31], v[64:67], v[88:91], v[16:31]
	ds_read2_b64 v[64:67], v106 offset0:160 offset1:162
	v_exp_f32_e32 v105, v75
	v_exp_f32_e32 v74, v76
	v_exp_f32_e32 v75, v77
	s_waitcnt lgkmcnt(0)
	v_mfma_f32_32x32x16_bf16 v[32:47], v[64:67], v[68:71], v[32:47]
	v_sub_f32_e32 v68, v73, v167
	v_sub_f32_e32 v69, v72, v167
	v_exp_f32_e32 v94, v69
	v_exp_f32_e32 v95, v68
	ds_read2_b64 v[68:71], v107 offset0:132 offset1:134
	v_cvt_pk_bf16_f32 v73, v104, v105
	v_cvt_pk_bf16_f32 v72, v94, v95
	v_mfma_f32_32x32x16_bf16 v[0:15], v[64:67], v[88:91], v[0:15]
	v_exp_f32_e32 v88, v78
	v_exp_f32_e32 v89, v79
	ds_read2_b64 v[76:79], v106 offset0:164 offset1:166
	v_cvt_pk_bf16_f32 v64, v80, v81
	v_cvt_pk_bf16_f32 v65, v82, v83
	v_cvt_pk_bf16_f32 v66, v84, v85
	v_cvt_pk_bf16_f32 v67, v86, v87
	v_pk_add_f32 v[80:81], v[102:103], v[74:75]
	v_cvt_pk_bf16_f32 v74, v74, v75
	v_cvt_pk_bf16_f32 v75, v88, v89
	s_waitcnt lgkmcnt(1)
	v_mfma_f32_32x32x16_bf16 v[48:63], v[68:71], v[64:67], v[48:63]
	v_add_f32_e64 v82, v100, v104
	v_add_f32_e64 v83, v101, v105
	v_mfma_f32_32x32x16_bf16 v[16:31], v[68:71], v[72:75], v[16:31]
	v_add_f32_e64 v68, v98, v94
	v_add_f32_e64 v69, v99, v95
	v_add_f32_e64 v70, v92, v88
	v_add_f32_e64 v71, v93, v89
	v_add_f32_e64 v68, v68, v80
	v_add_f32_e64 v69, v69, v81
	v_pk_add_f32 v[70:71], v[82:83], v[70:71]
	s_nop 0
	v_pk_add_f32 v[68:69], v[68:69], v[70:71]
	s_nop 0
	v_add_f32_e32 v68, v68, v69
	s_waitcnt lgkmcnt(0)
	v_mfma_f32_32x32x16_bf16 v[32:47], v[76:79], v[64:67], v[32:47]
	v_mov_b32_e32 v64, v68
	s_nop 1
	v_permlane32_swap_b32_e32 v64, v68
	v_add_f32_e32 v65, v96, v97
	v_add_f32_e32 v162, v162, v65
	s_waitcnt lgkmcnt(0)
	v_add_f32_e32 v64, v68, v64
	v_add_f32_e32 v160, v160, v64
	v_mfma_f32_32x32x16_bf16 v[0:15], v[76:79], v[72:75], v[0:15]
